# v88 + q_dec passes 2,3 moved into idle waves of the inverse-level slots + P2 step 2 tile rebalance (wave 0 takes QK tile (0,0), wave 7 takes A tile (3,3): max 3 tiles per wave)
# speedup vs baseline: 1.0102x; 1.0031x over previous
; #define LAS __attribute__((address_space(3)))
; template <int SKIP>
; __device__ __forceinline__ void p2_chunk_prep_fast(Frame& F, const Args& a) {
;     ...
;         PREP_LOAD(raw, cu + 1 < u_hi ? cu + 1 : cu);
;         const float gl = gc[63];
;         if (!(SKIP & 2)) {
;             const int kind = w >> 2, ti = w & 3;
;             bf16x8_t af[4];
; #pragma unroll
;             for (int ks = 0; ks < 4; ++ks) af[ks] = *(const LAS bf16x8_t*)(L + L_KS + (16 * ti + fr) * QS_LD + (32 * ks + 8 * fq) * 2);
;             bf16_t* oQK = QK + (size_t)cu * 4096;
; #pragma unroll
;             for (int tj = 0; tj < 4; ++tj) {
;                 if (kind == 0) {
;                     if (tj > ti) continue;
;                     f32x4 acc = (f32x4){0.f, 0.f, 0.f, 0.f};
; #pragma unroll
;                     for (int ks = 0; ks < 4; ++ks) acc = __builtin_amdgcn_mfma_f32_16x16x32_bf16(af[ks], *(const LAS bf16x8_t*)(L + L_KS + (16 * tj + fr) * QS_LD + (32 * ks + 8 * fq) * 2), acc, 0, 0, 0);
;                     const int j = 16 * tj + fr; const float gj = gc[j]; const f32x4 gi4 = *(const LAS f32x4*)(gc + 16 * ti + 4 * fq), bi4 = *(const LAS f32x4*)(beta + 16 * ti + 4 * fq);
; #pragma unroll
;                     for (int r = 0; r < 4; ++r) { const int i = 16 * ti + 4 * fq + r; const float m = (tj < ti || fr < 4 * fq + r) ? 1.f : 0.f; Am[i * AM_LD + j] = acc[r] * bi4[r] * __expf(fminf(gi4[r] - gj, 0.f)) * m; }
;                 } else {
;                     const int i = 16 * tj + fr; u32x2_t o = (u32x2_t){0u, 0u};
;                     if (tj >= ti) {
;                         f32x4 acc = (f32x4){0.f, 0.f, 0.f, 0.f};
; #pragma unroll
;                         for (int ks = 0; ks < 4; ++ks) acc = __builtin_amdgcn_mfma_f32_16x16x32_bf16(af[ks], *(const LAS bf16x8_t*)(L + L_QS + (16 * tj + fr) * QS_LD + (32 * ks + 8 * fq) * 2), acc, 0, 0, 0);
;                         const float gi = gc[i]; const f32x4 gj4 = *(const LAS f32x4*)(gc + 16 * ti + 4 * fq);
; #pragma unroll
;                         for (int r = 0; r < 4; ++r) { const float m = (tj > ti || 4 * fq + r <= fr) ? 1.f : 0.f; acc[r] = acc[r] * __expf(fminf(gi - gj4[r], 0.f)) * m; }
;                         o = pack4bf(acc);
;                     }
;                     *(u32x2_t*)(oQK + frag_off(i, 16 * ti + 4 * fq, 2)) = o;
;                 }
;             }
.LBB0_671:
	s_add_i32 s59, s84, 1
	s_cmp_ge_i32 s59, s16
	s_cselect_b64 s[8:9], -1, 0
	s_cmp_lt_i32 s59, s16
	s_cselect_b32 s6, s59, s84
	s_mul_hi_i32 s7, s6, 0x3e0f83e1
	s_ashr_i32 s85, s7, 3
	s_lshr_b32 s86, s7, 31
	s_add_i32 s85, s85, s86
	s_mul_i32 s87, s85, 33
	s_sub_i32 s87, s6, s87
	s_ashr_i32 s6, s85, 31
	s_lshr_b32 s6, s6, 28
	s_add_i32 s6, s85, s6
	s_and_b32 s6, s6, -16
	s_sub_i32 s6, s85, s6
	s_lshl_b32 s85, s6, 7
	s_lshr_b32 s7, s7, 7
	s_add_i32 s85, s85, s58
	s_add_i32 s7, s7, s86
	v_or_b32_e32 v4, s85, v119
	s_lshl_b32 s85, s87, 6
	s_sub_i32 s86, s85, 51
	s_lshl_b32 s7, s7, 11
	v_lshl_add_u32 v3, v78, 3, s86
	s_add_i32 s7, s7, -16
	v_mov_b32_e32 v46, s7
	v_cmp_lt_i32_e32 vcc, 15, v3
	v_ashrrev_i32_e32 v5, 31, v4
	v_max_i32_e32 v6, 0, v3
	v_cndmask_b32_e32 v7, v112, v46, vcc
	v_cmp_lt_i32_e32 vcc, 14, v3
	v_lshl_add_u64 v[4:5], v[4:5], 1, s[18:19]
	v_add_u32_e32 v6, v7, v6
	v_max_i32_e32 v8, -1, v3
	v_cndmask_b32_e32 v9, v112, v46, vcc
	v_mad_i64_i32 v[6:7], s[86:87], v6, s55, v[4:5]
	v_add3_u32 v8, v8, v9, 1
	s_waitcnt lgkmcnt(0)
	s_barrier
	v_mad_i64_i32 v[8:9], s[86:87], v8, s55, v[4:5]
	global_load_dwordx4 v[30:33], v[6:7], off nt
	global_load_dwordx4 v[38:41], v[8:9], off nt
	v_or_b32_e32 v6, 2, v3
	v_cmp_lt_i32_e32 vcc, 15, v6
	v_max_i32_e32 v7, 0, v6
	v_max_i32_e32 v8, -3, v3
	v_cndmask_b32_e32 v6, v112, v46, vcc
	v_cmp_lt_i32_e32 vcc, 12, v3
	v_add_u32_e32 v6, v6, v7
	v_mad_i64_i32 v[6:7], s[86:87], v6, s55, v[4:5]
	v_cndmask_b32_e32 v9, v112, v46, vcc
	v_add3_u32 v8, v8, v9, 3
	v_cmp_lt_i32_e32 vcc, 11, v3
	v_mad_i64_i32 v[8:9], s[86:87], v8, s55, v[4:5]
	global_load_dwordx4 v[34:37], v[6:7], off nt
	global_load_dwordx4 v[42:45], v[8:9], off nt
	v_max_i32_e32 v6, -4, v3
	v_cndmask_b32_e32 v7, v112, v46, vcc
	v_cmp_lt_i32_e32 vcc, 10, v3
	v_add3_u32 v6, v6, v7, 4
	v_max_i32_e32 v8, -5, v3
	v_cndmask_b32_e32 v9, v112, v46, vcc
	v_mad_i64_i32 v[6:7], s[86:87], v6, s55, v[4:5]
	v_add3_u32 v8, v8, v9, 5
	v_cmp_lt_i32_e32 vcc, 9, v3
	v_mad_i64_i32 v[8:9], s[86:87], v8, s55, v[4:5]
	global_load_dwordx4 v[26:29], v[6:7], off nt
	global_load_dwordx4 v[22:25], v[8:9], off nt
	v_max_i32_e32 v6, -6, v3
	v_cndmask_b32_e32 v7, v112, v46, vcc
	v_cmp_lt_i32_e32 vcc, 8, v3
	v_add3_u32 v6, v6, v7, 6
	v_max_i32_e32 v8, -7, v3
	v_cndmask_b32_e32 v9, v112, v46, vcc
	v_mad_i64_i32 v[6:7], s[86:87], v6, s55, v[4:5]
	v_add3_u32 v8, v8, v9, 7
	v_cmp_lt_i32_e32 vcc, 7, v3
	v_mad_i64_i32 v[8:9], s[86:87], v8, s55, v[4:5]
	global_load_dwordx4 v[18:21], v[6:7], off nt
	global_load_dwordx4 v[14:17], v[8:9], off nt
	v_cndmask_b32_e32 v7, v112, v46, vcc
	v_cmp_lt_i32_e32 vcc, 6, v3
	v_max_i32_e32 v6, -8, v3
	v_max_i32_e32 v8, -9, v3
	v_cndmask_b32_e32 v9, v112, v46, vcc
	v_cmp_lt_i32_e32 vcc, 5, v3
	v_max_i32_e32 v47, -10, v3
	v_add_u32_e32 v2, s85, v2
	v_cndmask_b32_e32 v3, v112, v46, vcc
	v_add3_u32 v6, v6, v7, 8
	v_add3_u32 v8, v8, v9, 9
	v_add3_u32 v3, v47, v3, 10
	v_cmp_lt_i32_e32 vcc, 15, v2
	v_mad_i64_i32 v[6:7], s[86:87], v6, s55, v[4:5]
	v_mad_i64_i32 v[8:9], s[86:87], v8, s55, v[4:5]
	v_mad_i64_i32 v[4:5], s[86:87], v3, s55, v[4:5]
	v_max_i32_e32 v3, 0, v2
	v_cndmask_b32_e32 v2, v112, v46, vcc
	v_add_u32_e32 v2, v2, v3
	v_ashrrev_i32_e32 v3, 31, v2
	v_lshlrev_b64 v[2:3], 7, v[2:3]
	v_lshl_add_u64 v[2:3], s[20:21], 0, v[2:3]
	s_ashr_i32 s7, s6, 31
	global_load_dwordx4 v[10:13], v[6:7], off nt
	s_nop 0
	global_load_dwordx4 v[6:9], v[8:9], off nt
	v_lshl_add_u64 v[46:47], s[6:7], 2, v[2:3]
	global_load_dwordx4 v[2:5], v[4:5], off nt
	s_nop 0
	global_load_dword v106, v[46:47], off
	global_load_dword v81, v[46:47], off offset:64
	v_and_b32_e32 v66, -16, v117
	v_or_b32_e32 v47, s61, v83
	v_add_u32_e32 v72, 0, v66
	v_mov_b32_e32 v46, s62
	v_mad_u32_u24 v47, v47, s28, v72
	ds_read_b32 v71, v46
	ds_read_b128 v[58:61], v47 offset:17408
	ds_read_b128 v[54:57], v47 offset:17472
	ds_read_b128 v[50:53], v47 offset:17536
	ds_read_b128 v[46:49], v47 offset:17600
	v_lshlrev_b32_e32 v67, 2, v118
	v_add_u32_e32 v62, s61, v67
	s_ashr_i32 s85, s84, 31
	v_lshlrev_b32_e32 v63, 4, v62
	v_lshlrev_b32_e32 v62, 1, v62
	s_lshl_b64 s[86:87], s[84:85], 13
	v_readlane_b32 s6, v255, 34
	v_and_or_b32 v62, v62, 48, v83
	s_add_u32 s88, s6, s86
	v_readlane_b32 s6, v255, 35
	v_lshlrev_b32_e32 v69, 4, v118
	v_and_b32_e32 v63, 0xfffffe00, v63
	v_lshlrev_b32_e32 v62, 3, v62
	v_and_b32_e32 v68, 4, v67
	s_addc_u32 s89, s6, s87
	v_add_u32_e32 v75, s97, v69
	v_or3_b32 v62, v62, v63, v68
	s_mov_b64 s[6:7], -1
	v_readlane_b32 s100, v255, 19
	s_cmp_eq_u32 s100, 4
	s_cbranch_scc1 .Lst2_skip1
	s_cmp_eq_u32 s100, 0
	s_cbranch_scc1 .Lst2_do1
	s_and_b64 vcc, exec, s[38:39]
	s_cbranch_vccz .LBB0_675
.Lst2_do1:
	v_mov_b32_e32 v64, 0
	s_andn2_b64 vcc, exec, s[68:69]
	v_mov_b32_e32 v65, 0
	s_cbranch_vccnz .LBB0_674
	v_mad_u32_u24 v63, v83, s28, v72
	ds_read_b128 v[84:87], v63
	ds_read_b128 v[88:91], v63 offset:64
	v_lshl_add_u32 v64, v83, 2, 0
	v_add_u32_e32 v64, 0x20500, v64
	ds_read_b128 v[92:95], v75
	s_waitcnt lgkmcnt(2)
	v_mfma_f32_16x16x32_bf16 v[84:87], v[58:61], v[84:87], 0
	ds_read_b32 v70, v64
	ds_read_b128 v[96:99], v63 offset:128
	ds_read_b128 v[100:103], v63 offset:192
	v_cmp_gt_i32_e32 vcc, v83, v67
	v_or_b32_e32 v73, 2, v67
	s_waitcnt lgkmcnt(4)
	v_mfma_f32_16x16x32_bf16 v[84:87], v[54:57], v[88:91], v[84:87]
	s_waitcnt lgkmcnt(2)
	v_sub_f32_e32 v63, v70, v92
	v_sub_f32_e32 v64, v70, v93
	v_min_f32_e32 v63, 0, v63
	s_waitcnt lgkmcnt(1)
	v_mfma_f32_16x16x32_bf16 v[84:87], v[50:53], v[96:99], v[84:87]
	v_min_f32_e32 v65, 0, v64
	v_mul_f32_e32 v63, 0x3fb8aa3b, v63
	v_exp_f32_e32 v64, v63
	v_mul_f32_e32 v63, 0x3fb8aa3b, v65
	s_waitcnt lgkmcnt(0)
	v_mfma_f32_16x16x32_bf16 v[84:87], v[46:49], v[100:103], v[84:87]
	v_exp_f32_e32 v65, v63
	v_sub_f32_e32 v74, v70, v94
	v_sub_f32_e32 v70, v70, v95
	v_cndmask_b32_e64 v77, 0, 1.0, vcc
	v_cmp_gt_i32_e32 vcc, v67, v83
	v_min_f32_e32 v74, 0, v74
	v_min_f32_e32 v70, 0, v70
	v_cndmask_b32_e64 v76, 1.0, 0, vcc
	v_pk_mul_f32 v[64:65], v[84:85], v[64:65]
	v_mul_f32_e32 v74, 0x3fb8aa3b, v74
	v_mul_f32_e32 v70, 0x3fb8aa3b, v70
	v_pk_mul_f32 v[64:65], v[76:77], v[64:65]
	v_exp_f32_e32 v76, v74
	v_exp_f32_e32 v77, v70
	v_or_b32_e32 v63, 3, v67
	v_cmp_gt_i32_e32 vcc, v63, v83
	v_cvt_pk_bf16_f32 v64, v64, v65
	v_pk_mul_f32 v[76:77], v[86:87], v[76:77]
	v_cndmask_b32_e64 v85, 1.0, 0, vcc
	v_cmp_gt_i32_e32 vcc, v73, v83
	s_nop 1
	v_cndmask_b32_e64 v84, 1.0, 0, vcc
	v_pk_mul_f32 v[76:77], v[84:85], v[76:77]
	s_nop 0
	v_cvt_pk_bf16_f32 v65, v76, v77
.LBB0_674:
	v_ashrrev_i32_e32 v63, 31, v62
	v_lshl_add_u64 v[76:77], v[62:63], 1, s[88:89]
	s_cmp_lg_u32 s100, 0
	s_cselect_b64 s[6:7], 0, -1
	global_store_dwordx2 v[76:77], v[64:65], off
	s_branch .LBB0_675
.Lst2_skip1:
	s_mov_b64 s[6:7], 0

; #define LAS __attribute__((address_space(3)))
; template <int SKIP>
; __device__ __forceinline__ void p2_chunk_prep_fast(Frame& F, const Args& a) {
;     ...
;             for (int tj = 0; tj < 4; ++tj) {
;                 if (kind == 0) {
;                     if (tj > ti) continue;
;                     f32x4 acc = (f32x4){0.f, 0.f, 0.f, 0.f};
; #pragma unroll
;                     for (int ks = 0; ks < 4; ++ks) acc = __builtin_amdgcn_mfma_f32_16x16x32_bf16(af[ks], *(const LAS bf16x8_t*)(L + L_KS + (16 * tj + fr) * QS_LD + (32 * ks + 8 * fq) * 2), acc, 0, 0, 0);
;                     const int j = 16 * tj + fr; const float gj = gc[j]; const f32x4 gi4 = *(const LAS f32x4*)(gc + 16 * ti + 4 * fq), bi4 = *(const LAS f32x4*)(beta + 16 * ti + 4 * fq);
; #pragma unroll
;                     for (int r = 0; r < 4; ++r) { const int i = 16 * ti + 4 * fq + r; const float m = (tj < ti || fr < 4 * fq + r) ? 1.f : 0.f; Am[i * AM_LD + j] = acc[r] * bi4[r] * __expf(fminf(gi4[r] - gj, 0.f)) * m; }
.LBB0_693:
	v_readlane_b32 s100, v255, 19
	s_cmp_eq_u32 s100, 3
	s_cselect_b64 s[6:7], 0, s[6:7]
	s_cmp_lg_u32 s100, 7
	s_cbranch_scc1 .Lst2_not7
	s_mov_b64 s[6:7], -1
	v_subrev_u32_e32 v69, 64, v69
	v_subrev_u32_e32 v73, 0x100, v73
	v_subrev_u32_e32 v74, 0x100, v74

; #define LAS __attribute__((address_space(3)))
; template <int SKIP>
; __device__ __forceinline__ void p2_chunk_prep_fast(Frame& F, const Args& a) {
;     ...
;             for (int tj = 0; tj < 4; ++tj) {
;                 if (kind == 0) {
;                     if (tj > ti) continue;
;                     f32x4 acc = (f32x4){0.f, 0.f, 0.f, 0.f};
; #pragma unroll
;                     for (int ks = 0; ks < 4; ++ks) acc = __builtin_amdgcn_mfma_f32_16x16x32_bf16(af[ks], *(const LAS bf16x8_t*)(L + L_KS + (16 * tj + fr) * QS_LD + (32 * ks + 8 * fq) * 2), acc, 0, 0, 0);
;                     const int j = 16 * tj + fr; const float gj = gc[j]; const f32x4 gi4 = *(const LAS f32x4*)(gc + 16 * ti + 4 * fq), bi4 = *(const LAS f32x4*)(beta + 16 * ti + 4 * fq);
; #pragma unroll
;                     for (int r = 0; r < 4; ++r) { const int i = 16 * ti + 4 * fq + r; const float m = (tj < ti || fr < 4 * fq + r) ? 1.f : 0.f; Am[i * AM_LD + j] = acc[r] * bi4[r] * __expf(fminf(gi4[r] - gj, 0.f)) * m; }
.LBB0_696:
	s_cmp_lg_u32 s100, 7
	s_cbranch_scc1 .Lst2_r7
	v_add_u32_e32 v69, 64, v69

; __device__ __forceinline__ u32x4 pack8(f32x4 v0, f32x4 v1) { u32x4 w; w.x = cvt_pk_bf16(v0[0], v0[1]); w.y = cvt_pk_bf16(v0[2], v0[3]); w.z = cvt_pk_bf16(v1[0], v1[1]); w.w = cvt_pk_bf16(v1[2], v1[3]); return w; }
; #define LAS __attribute__((address_space(3)))
; __device__ __forceinline__ int frag_off(int row, int k, int ksteps) { return ((row >> 4) * ksteps + (k >> 5)) * 512 + (((k >> 3) & 3) * 16 + (row & 15)) * 8 + (k & 7); }
; template <int SKIP>
; __device__ __forceinline__ void p2_chunk_prep_fast(Frame& F, const Args& a) {
;     ...
;             bf16_t *oQD = QD + (size_t)cu * 8192, *oKDT = KDT + (size_t)cu * 8192;
;             for (int idx = tid - 64; idx < 2048; idx += 448) {
;                 if (idx < 1024) { const int i = idx >> 4, d8 = (idx & 15) * 8; pg8::f32x4 x0, x1; pg8::unpack8(*(const LAS pg8::u32x4*)(L + L_QS + i * QS_LD + d8 * 2), x0, x1);
;                     const float e = __expf(gc[i]); *(pg8::u32x4*)(oQD + frag_off(i, d8, 4)) = pg8::pack8(x0 * e, x1 * e); }
.LBB0_699:
	s_or_b64 exec, exec, s[94:95]
	s_movk_i32 s94, 0xffff
	v_cmp_lt_i32_e32 vcc, s94, v48
	v_add_u32_e32 v46, 0x1c0, v46
	s_or_b64 s[92:93], vcc, s[92:93]
	v_add_u32_e32 v47, 0xe00, v47
	s_andn2_b64 exec, exec, s[92:93]
	s_cbranch_execz .LBB0_704

; __device__ __forceinline__ u32x4 pack8(f32x4 v0, f32x4 v1) { u32x4 w; w.x = cvt_pk_bf16(v0[0], v0[1]); w.y = cvt_pk_bf16(v0[2], v0[3]); w.z = cvt_pk_bf16(v1[0], v1[1]); w.w = cvt_pk_bf16(v1[2], v1[3]); return w; }
; #define LAS __attribute__((address_space(3)))
; __device__ __forceinline__ int frag_off(int row, int k, int ksteps) { return ((row >> 4) * ksteps + (k >> 5)) * 512 + (((k >> 3) & 3) * 16 + (row & 15)) * 8 + (k & 7); }
; template <int SKIP>
; __device__ __forceinline__ void p2_chunk_prep_fast(Frame& F, const Args& a) {
;     ...
;                 if (idx < 1024) { const int i = idx >> 4, d8 = (idx & 15) * 8; pg8::f32x4 x0, x1; pg8::unpack8(*(const LAS pg8::u32x4*)(L + L_QS + i * QS_LD + d8 * 2), x0, x1);
;                     const float e = __expf(gc[i]); *(pg8::u32x4*)(oQD + frag_off(i, d8, 4)) = pg8::pack8(x0 * e, x1 * e); }
.Lkd_slot2:
	v_readlane_b32 s88, v255, 19
	s_cmp_lt_u32 s88, 3
	s_cbranch_scc1 .Lqd_slot2
	v_add_u32_e32 v159, 0x50, v154
	v_lshrrev_b32_e32 v172, 3, v159
	v_xor_b32_e32 v172, v172, v153
	v_and_b32_e32 v172, 7, v172
	v_lshlrev_b32_e32 v172, 4, v172
	v_mad_u32_u24 v172, v159, s30, v172
	ds_read_b128 v[176:179], v172 offset:34816
	v_readlane_b32 s88, v255, 25
	v_readlane_b32 s89, v255, 31
	s_lshl_b32 s90, s84, 14
	s_add_u32 s88, s88, s90
	s_addc_u32 s89, s89, 0
	s_waitcnt lgkmcnt(0)
	v_lshrrev_b32_e32 v188, 4, v159
	v_and_b32_e32 v189, 15, v159
	v_lshlrev_b32_e32 v188, 10, v188
	v_lshl_add_u32 v188, v189, 3, v188
	v_add_lshl_u32 v188, v188, v155, 1
	v_lshlrev_b32_e32 v216, 16, v176
	v_and_b32_e32 v217, 0xffff0000, v176
	v_lshlrev_b32_e32 v218, 16, v177
	v_and_b32_e32 v219, 0xffff0000, v177
	v_lshlrev_b32_e32 v220, 16, v178
	v_and_b32_e32 v221, 0xffff0000, v178
	v_lshlrev_b32_e32 v222, 16, v179
	v_and_b32_e32 v223, 0xffff0000, v179
	v_pk_mul_f32 v[216:217], v[180:181], v[216:217]
	v_pk_mul_f32 v[218:219], v[182:183], v[218:219]
	v_pk_mul_f32 v[220:221], v[184:185], v[220:221]
	v_pk_mul_f32 v[222:223], v[186:187], v[222:223]
	s_nop 0
	v_cvt_pk_bf16_f32 v224, v216, v217
	v_cvt_pk_bf16_f32 v225, v218, v219
	v_cvt_pk_bf16_f32 v226, v220, v221
	v_cvt_pk_bf16_f32 v227, v222, v223
	s_nop 0
	global_store_dwordx4 v188, v[224:227], s[88:89]
	s_branch .LBB0_713
.Lqd_slot2:
	v_add_u32_e32 v152, 0x3c0, v254
	v_lshrrev_b32_e32 v154, 4, v152
	v_and_b32_e32 v156, 15, v152
	v_lshlrev_b32_e32 v158, 4, v156
	v_mad_u32_u24 v158, v154, s28, v158
	v_lshlrev_b32_e32 v160, 2, v154
	v_add_u32_e32 v160, 0x20500, v160
	ds_read_b32 v172, v160
	ds_read_b128 v[164:167], v158
	v_lshrrev_b32_e32 v176, 4, v154
	v_lshrrev_b32_e32 v177, 2, v156
	v_lshl_add_u32 v176, v176, 2, v177
	v_and_b32_e32 v177, 3, v156
	v_and_b32_e32 v178, 15, v154
	v_lshl_add_u32 v177, v177, 4, v178
	v_lshlrev_b32_e32 v177, 3, v177
	v_lshl_add_u32 v176, v176, 9, v177
	v_lshlrev_b32_e32 v176, 1, v176
	v_readlane_b32 s88, v255, 54
	v_readlane_b32 s89, v255, 55
	s_lshl_b64 s[90:91], s[86:87], 1
	s_add_u32 s88, s88, s90
	s_addc_u32 s89, s89, s91
	s_waitcnt lgkmcnt(0)
	v_mul_f32_e32 v172, 0x3fb8aa3b, v172
	v_exp_f32_e32 v172, v172
	v_lshlrev_b32_e32 v216, 16, v164
	v_and_b32_e32 v217, 0xffff0000, v164
	v_lshlrev_b32_e32 v218, 16, v165
	v_and_b32_e32 v219, 0xffff0000, v165
	v_lshlrev_b32_e32 v220, 16, v166
	v_and_b32_e32 v221, 0xffff0000, v166
	v_lshlrev_b32_e32 v222, 16, v167
	v_and_b32_e32 v223, 0xffff0000, v167
	v_pk_mul_f32 v[216:217], v[172:173], v[216:217] op_sel_hi:[0,1]
	v_pk_mul_f32 v[218:219], v[172:173], v[218:219] op_sel_hi:[0,1]
	v_pk_mul_f32 v[220:221], v[172:173], v[220:221] op_sel_hi:[0,1]
	v_pk_mul_f32 v[222:223], v[172:173], v[222:223] op_sel_hi:[0,1]
	s_nop 0
	v_cvt_pk_bf16_f32 v224, v216, v217
	v_cvt_pk_bf16_f32 v225, v218, v219
	v_cvt_pk_bf16_f32 v226, v220, v221
	v_cvt_pk_bf16_f32 v227, v222, v223
	s_nop 0
	global_store_dwordx4 v176, v[224:227], s[88:89]

; __device__ __forceinline__ u32x4 pack8(f32x4 v0, f32x4 v1) { u32x4 w; w.x = cvt_pk_bf16(v0[0], v0[1]); w.y = cvt_pk_bf16(v0[2], v0[3]); w.z = cvt_pk_bf16(v1[0], v1[1]); w.w = cvt_pk_bf16(v1[2], v1[3]); return w; }
; #define LAS __attribute__((address_space(3)))
; __device__ __forceinline__ int frag_off(int row, int k, int ksteps) { return ((row >> 4) * ksteps + (k >> 5)) * 512 + (((k >> 3) & 3) * 16 + (row & 15)) * 8 + (k & 7); }
; template <int SKIP>
; __device__ __forceinline__ void p2_chunk_prep_fast(Frame& F, const Args& a) {
;     ...
;                 if (idx < 1024) { const int i = idx >> 4, d8 = (idx & 15) * 8; pg8::f32x4 x0, x1; pg8::unpack8(*(const LAS pg8::u32x4*)(L + L_QS + i * QS_LD + d8 * 2), x0, x1);
;                     const float e = __expf(gc[i]); *(pg8::u32x4*)(oQD + frag_off(i, d8, 4)) = pg8::pack8(x0 * e, x1 * e); }
;                 else { const int id = idx - 1024, d = id >> 3, i8 = (id & 7) * 8; pg8::f32x4 x0, x1; pg8::unpack8(*(const LAS pg8::u32x4*)(L + L_KT + ktoff(d, i8 >> 3)), x0, x1);
; #pragma unroll
;                     for (int j = 0; j < 4; ++j) { x0[j] *= __expf(gl - gc[i8 + j]); x1[j] *= __expf(gl - gc[i8 + 4 + j]); }
;                     *(pg8::u32x4*)(oKDT + frag_off(d, i8, 2)) = pg8::pack8(x0, x1); }
.Lkd_slot3:
	v_readlane_b32 s88, v255, 19
	s_cmp_eq_u32 s88, 3
	s_cbranch_scc1 .Lkd3_k
	s_cmp_lt_u32 s88, 3
	s_cbranch_scc1 .Lqd3_two
	s_lshl_b32 s90, s88, 6
	s_add_i32 s90, s90, 0x1c0
	v_add_u32_e32 v152, s90, v254
	v_lshrrev_b32_e32 v154, 4, v152
	v_and_b32_e32 v156, 15, v152
	v_lshlrev_b32_e32 v158, 4, v156
	v_mad_u32_u24 v158, v154, s28, v158
	v_lshlrev_b32_e32 v160, 2, v154
	v_add_u32_e32 v160, 0x20500, v160
	ds_read_b32 v172, v160
	ds_read_b128 v[164:167], v158
	v_lshrrev_b32_e32 v176, 4, v154
	v_lshrrev_b32_e32 v177, 2, v156
	v_lshl_add_u32 v176, v176, 2, v177
	v_and_b32_e32 v177, 3, v156
	v_and_b32_e32 v178, 15, v154
	v_lshl_add_u32 v177, v177, 4, v178
	v_lshlrev_b32_e32 v177, 3, v177
	v_lshl_add_u32 v176, v176, 9, v177
	v_lshlrev_b32_e32 v176, 1, v176
	v_readlane_b32 s88, v255, 54
	v_readlane_b32 s89, v255, 55
	s_lshl_b64 s[90:91], s[86:87], 1
	s_add_u32 s88, s88, s90
	s_addc_u32 s89, s89, s91
	s_waitcnt lgkmcnt(0)
	v_mul_f32_e32 v172, 0x3fb8aa3b, v172
	v_exp_f32_e32 v172, v172
	v_lshlrev_b32_e32 v216, 16, v164
	v_and_b32_e32 v217, 0xffff0000, v164
	v_lshlrev_b32_e32 v218, 16, v165
	v_and_b32_e32 v219, 0xffff0000, v165
	v_lshlrev_b32_e32 v220, 16, v166
	v_and_b32_e32 v221, 0xffff0000, v166
	v_lshlrev_b32_e32 v222, 16, v167
	v_and_b32_e32 v223, 0xffff0000, v167
	v_pk_mul_f32 v[216:217], v[172:173], v[216:217] op_sel_hi:[0,1]
	v_pk_mul_f32 v[218:219], v[172:173], v[218:219] op_sel_hi:[0,1]
	v_pk_mul_f32 v[220:221], v[172:173], v[220:221] op_sel_hi:[0,1]
	v_pk_mul_f32 v[222:223], v[172:173], v[222:223] op_sel_hi:[0,1]
	s_nop 0
	v_cvt_pk_bf16_f32 v224, v216, v217
	v_cvt_pk_bf16_f32 v225, v218, v219
	v_cvt_pk_bf16_f32 v226, v220, v221
	v_cvt_pk_bf16_f32 v227, v222, v223
	s_nop 0
	global_store_dwordx4 v176, v[224:227], s[88:89]
	s_branch .LBB0_715
.Lqd3_two:
	s_lshl_b32 s90, s88, 7
	s_add_i32 s90, s90, 0x140
	v_add_u32_e32 v152, s90, v254
	v_add_u32_e32 v153, 64, v152
	v_lshrrev_b32_e32 v154, 4, v152
	v_and_b32_e32 v156, 15, v152
	v_lshlrev_b32_e32 v158, 4, v156
	v_mad_u32_u24 v158, v154, s28, v158
	v_lshlrev_b32_e32 v160, 2, v154
	v_add_u32_e32 v160, 0x20500, v160
	ds_read_b32 v172, v160
	ds_read_b128 v[164:167], v158
	v_lshrrev_b32_e32 v155, 4, v153
	v_and_b32_e32 v157, 15, v153
	v_lshlrev_b32_e32 v159, 4, v157
	v_mad_u32_u24 v159, v155, s28, v159
	v_lshlrev_b32_e32 v161, 2, v155
	v_add_u32_e32 v161, 0x20500, v161
	ds_read_b32 v174, v161
	ds_read_b128 v[168:171], v159
	v_lshrrev_b32_e32 v176, 4, v154
	v_lshrrev_b32_e32 v177, 2, v156
	v_lshl_add_u32 v176, v176, 2, v177
	v_and_b32_e32 v177, 3, v156
	v_and_b32_e32 v178, 15, v154
	v_lshl_add_u32 v177, v177, 4, v178
	v_lshlrev_b32_e32 v177, 3, v177
	v_lshl_add_u32 v176, v176, 9, v177
	v_lshlrev_b32_e32 v176, 1, v176
	v_lshrrev_b32_e32 v180, 4, v155
	v_lshrrev_b32_e32 v181, 2, v157
	v_lshl_add_u32 v180, v180, 2, v181
	v_and_b32_e32 v181, 3, v157
	v_and_b32_e32 v182, 15, v155
	v_lshl_add_u32 v181, v181, 4, v182
	v_lshlrev_b32_e32 v181, 3, v181
	v_lshl_add_u32 v180, v180, 9, v181
	v_lshlrev_b32_e32 v180, 1, v180
	v_readlane_b32 s88, v255, 54
	v_readlane_b32 s89, v255, 55
	s_lshl_b64 s[90:91], s[86:87], 1
	s_add_u32 s88, s88, s90
	s_addc_u32 s89, s89, s91
	s_waitcnt lgkmcnt(2)
	v_mul_f32_e32 v172, 0x3fb8aa3b, v172
	v_exp_f32_e32 v172, v172
	v_lshlrev_b32_e32 v216, 16, v164
	v_and_b32_e32 v217, 0xffff0000, v164
	v_lshlrev_b32_e32 v218, 16, v165
	v_and_b32_e32 v219, 0xffff0000, v165
	v_lshlrev_b32_e32 v220, 16, v166
	v_and_b32_e32 v221, 0xffff0000, v166
	v_lshlrev_b32_e32 v222, 16, v167
	v_and_b32_e32 v223, 0xffff0000, v167
	v_pk_mul_f32 v[216:217], v[172:173], v[216:217] op_sel_hi:[0,1]
	v_pk_mul_f32 v[218:219], v[172:173], v[218:219] op_sel_hi:[0,1]
	v_pk_mul_f32 v[220:221], v[172:173], v[220:221] op_sel_hi:[0,1]
	v_pk_mul_f32 v[222:223], v[172:173], v[222:223] op_sel_hi:[0,1]
	s_nop 0
	v_cvt_pk_bf16_f32 v224, v216, v217
	v_cvt_pk_bf16_f32 v225, v218, v219
	v_cvt_pk_bf16_f32 v226, v220, v221
	v_cvt_pk_bf16_f32 v227, v222, v223
	s_nop 0
	global_store_dwordx4 v176, v[224:227], s[88:89]
	s_waitcnt lgkmcnt(0)
	v_mul_f32_e32 v174, 0x3fb8aa3b, v174
	v_exp_f32_e32 v174, v174
	v_lshlrev_b32_e32 v216, 16, v168
	v_and_b32_e32 v217, 0xffff0000, v168
	v_lshlrev_b32_e32 v218, 16, v169
	v_and_b32_e32 v219, 0xffff0000, v169
	v_lshlrev_b32_e32 v220, 16, v170
	v_and_b32_e32 v221, 0xffff0000, v170
	v_lshlrev_b32_e32 v222, 16, v171
	v_and_b32_e32 v223, 0xffff0000, v171
	v_pk_mul_f32 v[216:217], v[174:175], v[216:217] op_sel_hi:[0,1]
	v_pk_mul_f32 v[218:219], v[174:175], v[218:219] op_sel_hi:[0,1]
	v_pk_mul_f32 v[220:221], v[174:175], v[220:221] op_sel_hi:[0,1]
	v_pk_mul_f32 v[222:223], v[174:175], v[222:223] op_sel_hi:[0,1]
	s_nop 0
	v_cvt_pk_bf16_f32 v224, v216, v217
	v_cvt_pk_bf16_f32 v225, v218, v219
	v_cvt_pk_bf16_f32 v226, v220, v221
	v_cvt_pk_bf16_f32 v227, v222, v223
	s_nop 0
	global_store_dwordx4 v180, v[224:227], s[88:89]
	s_branch .LBB0_715
.Lkd3_k:
	v_add_u32_e32 v159, 0x78, v154
	v_lshrrev_b32_e32 v172, 3, v159
	v_xor_b32_e32 v172, v172, v153
	v_and_b32_e32 v172, 7, v172
	v_lshlrev_b32_e32 v172, 4, v172
	v_mad_u32_u24 v172, v159, s30, v172
	ds_read_b128 v[176:179], v172 offset:34816
	v_readlane_b32 s88, v255, 25
	v_readlane_b32 s89, v255, 31
	s_lshl_b32 s90, s84, 14
	s_add_u32 s88, s88, s90
	s_addc_u32 s89, s89, 0
	s_waitcnt lgkmcnt(0)
	v_lshrrev_b32_e32 v188, 4, v159
	v_and_b32_e32 v189, 15, v159
	v_lshlrev_b32_e32 v188, 10, v188
	v_lshl_add_u32 v188, v189, 3, v188
	v_add_lshl_u32 v188, v188, v155, 1
	v_lshlrev_b32_e32 v216, 16, v176
	v_and_b32_e32 v217, 0xffff0000, v176
	v_lshlrev_b32_e32 v218, 16, v177
	v_and_b32_e32 v219, 0xffff0000, v177
	v_lshlrev_b32_e32 v220, 16, v178
	v_and_b32_e32 v221, 0xffff0000, v178
	v_lshlrev_b32_e32 v222, 16, v179
	v_and_b32_e32 v223, 0xffff0000, v179
	v_pk_mul_f32 v[216:217], v[180:181], v[216:217]
	v_pk_mul_f32 v[218:219], v[182:183], v[218:219]
	v_pk_mul_f32 v[220:221], v[184:185], v[220:221]
	v_pk_mul_f32 v[222:223], v[186:187], v[222:223]
	s_nop 0
	v_cvt_pk_bf16_f32 v224, v216, v217
	v_cvt_pk_bf16_f32 v225, v218, v219
	v_cvt_pk_bf16_f32 v226, v220, v221
	v_cvt_pk_bf16_f32 v227, v222, v223
	s_nop 0
	global_store_dwordx4 v188, v[224:227], s[88:89]
